# XCD-affine item mapping also in phases 5 and 8 (dual item jp=q&3, mt=x+8*(q>>2); the 40 leftover single tiles on workgroups x<5,q<8 of the matching XCD)
# speedup vs baseline: 1.0479x; 1.0038x over previous
.LBB0_836:
	s_or_b64 exec, exec, s[0:1]
	s_add_u32 s3, s30, 0x14c0000
	s_addc_u32 s10, s31, 0
	s_abs_i32 s0, s84
	s_waitcnt vmcnt(0)
	v_cvt_f32_u32_e32 v0, s0
	s_sub_i32 s1, 0, s0
	s_waitcnt lgkmcnt(0)
	s_barrier
	v_rcp_iflag_f32_e32 v0, v0
	s_nop 0
	v_mul_f32_e32 v0, 0x4f7ffffe, v0
	v_cvt_u32_f32_e32 v0, v0
	s_nop 0
	v_readfirstlane_b32 s4, v0
	s_mul_i32 s1, s1, s4
	s_mul_hi_u32 s1, s4, s1
	s_add_i32 s4, s4, s1
	s_mul_hi_u32 s1, s4, 0x214
	s_mul_i32 s1, s1, s0
	s_sub_i32 s1, 0x214, s1
	s_sub_i32 s4, s1, s0
	s_cmp_ge_u32 s1, s0
	s_cselect_b32 s1, s4, s1
	s_sub_i32 s4, s1, s0
	s_cmp_ge_u32 s1, s0
	s_cselect_b32 s75, s4, s1
	s_sub_i32 s74, 0x214, s75
	s_cmp_lt_i32 s2, s74
	s_cselect_b64 s[8:9], -1, 0
	s_cmp_ge_i32 s2, s74
	s_cbranch_scc1 .LBB0_861
	v_and_b32_e32 v7, 48, v157
	v_lshlrev_b32_e32 v4, 4, v152
	v_sub_u32_e32 v7, 0, v7
	v_lshl_or_b32 v146, v154, 11, v4
	v_and_b32_e32 v4, 0x4f, v153
	v_and_b32_e32 v5, 0x1c0, v162
	v_bitop3_b32 v147, v153, 48, v7 bitop3:0x48
	s_add_u32 s0, s30, 0x27e0040
	v_xor_b32_e32 v0, v153, v166
	v_or_b32_e32 v6, v5, v159
	v_lshl_or_b32 v168, v4, 6, v147
	v_and_or_b32 v5, v155, 12, v5
	v_lshlrev_b32_e32 v4, 1, v4
	s_addc_u32 s1, s31, 0
	s_lshl_b32 s4, s2, 7
	v_lshlrev_b32_e32 v1, 5, v154
	v_lshlrev_b32_e32 v0, 3, v0
	v_lshl_or_b32 v169, v5, 8, v4
	v_or_b32_e32 v4, s4, v167
	v_or_b32_e32 v144, v1, v167
	v_and_b32_e32 v3, 24, v0
	v_add_u32_e32 v173, v4, v1
	v_lshlrev_b32_e32 v1, 15, v154
	v_or3_b32 v1, v1, v150, v3
	v_or_b32_e32 v145, 16, v144
	v_mov_b32_e32 v131, 0
	v_lshlrev_b32_e32 v130, 1, v1
	v_lshlrev_b32_e32 v1, 4, v159
	v_lshl_or_b32 v0, v144, 10, v3
	v_lshl_or_b32 v2, v145, 10, v3
	v_lshl_add_u64 v[132:133], s[30:31], 0, v[130:131]
	v_or_b32_e32 v130, 0x8000, v130
	v_lshl_or_b32 v175, v158, 8, v1
	v_lshlrev_b32_e32 v151, 6, v6
	v_or_b32_e32 v170, 32, v169
	v_or_b32_e32 v171, 64, v169
	v_or_b32_e32 v172, 0x60, v169
	v_mov_b32_e32 v129, v131
	s_lshl_b32 s11, s84, 7
	v_or_b32_e32 v174, 16, v173
	v_lshl_add_u64 v[134:135], s[30:31], 0, v[130:131]
	v_or_b32_e32 v176, s4, v158
	v_or_b32_e32 v177, 0x8000, v175
	v_mov_b32_e32 v178, 0x427f
	v_lshlrev_b32_e32 v179, 1, v3
	v_lshlrev_b32_e32 v180, 1, v0
	v_add_u32_e32 v181, 0x2000, v146
	v_add_u32_e32 v182, 0x4000, v146
	v_add_u32_e32 v183, 0x400, v146
	v_lshlrev_b32_e32 v184, 1, v2
	v_add_u32_e32 v185, 0x2400, v146
	v_add_u32_e32 v186, 0x4400, v146
	s_mov_b64 s[4:5], 0x14c0040
	s_mov_b64 s[6:7], 0x1500040
	s_movk_i32 s33, 0x407f
	s_mov_b32 s34, 0xfe03f81
	s_mov_b32 s35, s2
	s_cmp_eq_u32 s84, 0x200
	s_cbranch_scc0 .Lx6d_go
	s_and_b32 s12, s2, 7
	s_lshr_b32 s13, s2, 3
	s_and_b32 s35, s13, 3
	s_lshr_b32 s13, s13, 2
	s_mul_i32 s35, s35, 0x85
	s_lshl_b32 s13, s13, 3
	s_add_i32 s35, s35, s12
	s_add_i32 s35, s35, s13
	s_sub_i32 s12, s35, s2
	s_lshl_b32 s12, s12, 7
	v_add_u32_e32 v173, s12, v173
	v_add_u32_e32 v174, s12, v174
	v_add_u32_e32 v176, s12, v176
.Lx6d_go:
	s_branch .LBB0_839

.LBB0_861:
	s_lshl_b32 s76, s75, 1
	s_mov_b32 s21, s2
	s_cmp_eq_u32 s84, 0x200
	s_cbranch_scc0 .Lx6s_ent
	s_mov_b32 s21, 0x7fffffff
	s_cmp_lt_u32 s2, 64
	s_cbranch_scc0 .Lx6s_ent
	s_and_b32 s6, s2, 7
	s_cmp_lt_u32 s6, 5
	s_cbranch_scc0 .Lx6s_ent
	s_lshr_b32 s12, s2, 4
	s_mul_i32 s12, s12, 0x85
	s_add_i32 s12, s12, s6
	s_addk_i32 s12, 0xfe80
	s_lshl_b32 s12, s12, 1
	s_bfe_u32 s6, s2, 0x10003
	s_or_b32 s21, s12, s6
.Lx6s_ent:
	s_cmp_lt_i32 s21, s76
	s_cselect_b64 s[16:17], -1, 0
	s_cmp_ge_i32 s21, s76
	s_cbranch_scc1 .LBB0_876
	v_lshlrev_b32_e32 v7, 4, v152
	v_lshl_or_b32 v94, v154, 12, v7
	v_and_b32_e32 v7, 0x4f, v153
	v_and_b32_e32 v8, 0x1c0, v162
	s_add_u32 s0, s30, 0x27e0080
	v_lshl_or_b32 v90, v154, 5, v163
	v_or_b32_e32 v9, v8, v159
	v_lshlrev_b32_e32 v97, 7, v7
	v_and_or_b32 v8, v155, 12, v8
	v_lshlrev_b32_e32 v7, 1, v7
	s_addc_u32 s1, s31, 0
	s_lshl_b32 s6, s75, 7
	v_lshlrev_b32_e32 v0, 3, v164
	v_or_b32_e32 v91, 8, v90
	v_lshl_or_b32 v99, v8, 8, v7
	v_subrev_u32_e32 v7, s6, v90
	v_and_b32_e32 v1, 56, v0
	v_lshrrev_b32_e32 v2, 1, v91
	v_add_u32_e32 v100, 0x10a00, v7
	v_add_u32_e32 v101, 0x10a08, v7
	v_add_u32_e32 v102, 0x10a10, v7
	v_add_u32_e32 v103, 0x10a18, v7
	v_lshl_or_b32 v7, v154, 15, v149
	v_xor_b32_e32 v2, v2, v153
	v_or_b32_e32 v8, v7, v1
	v_lshlrev_b32_e32 v2, 3, v2
	v_mov_b32_e32 v65, 0
	v_lshlrev_b32_e32 v64, 1, v8
	v_and_b32_e32 v3, 56, v2
	v_or_b32_e32 v93, 24, v90
	v_lshlrev_b32_e32 v96, 7, v9
	v_lshl_add_u64 v[8:9], s[30:31], 0, v[64:65]
	s_mov_b64 s[4:5], 0x14c0080
	v_lshrrev_b32_e32 v5, 1, v93
	v_lshl_add_u64 v[66:67], v[8:9], 0, s[4:5]
	v_or_b32_e32 v8, v7, v3
	v_mov_b32_e32 v9, 0x4000
	v_xor_b32_e32 v5, v5, v153
	v_lshl_or_b32 v8, v8, 1, v9
	v_mov_b32_e32 v9, v65
	v_lshlrev_b32_e32 v5, 3, v5
	v_lshl_add_u64 v[8:9], s[30:31], 0, v[8:9]
	v_or_b32_e32 v64, 0x8000, v64
	v_and_b32_e32 v5, 56, v5
	v_lshl_add_u64 v[68:69], v[8:9], 0, s[4:5]
	v_lshl_add_u64 v[8:9], s[30:31], 0, v[64:65]
	v_lshl_add_u64 v[70:71], v[8:9], 0, s[4:5]
	v_or_b32_e32 v7, v7, v5
	v_mov_b32_e32 v8, 0xc000
	v_or_b32_e32 v92, 16, v90
	v_lshl_or_b32 v64, v7, 1, v8
	v_lshl_or_b32 v0, v90, 10, v1
	v_lshl_or_b32 v2, v91, 10, v3
	v_lshl_or_b32 v4, v92, 10, v1
	v_lshl_or_b32 v6, v93, 10, v5
	v_bitop3_b32 v10, v160, v162, 7 bitop3:0x78
	v_lshl_add_u64 v[8:9], s[30:31], 0, v[64:65]
	v_lshlrev_b32_e32 v7, 4, v159
	v_lshlrev_b32_e32 v95, 4, v10
	v_lshlrev_b32_e32 v98, 4, v161
	s_lshl_b32 s11, s21, 7
	s_lshl_b32 s12, s84, 7
	v_lshl_add_u64 v[72:73], v[8:9], 0, s[4:5]
	v_lshl_or_b32 v104, v158, 8, v7
	v_subrev_u32_e32 v105, s6, v158
	v_mov_b32_e32 v106, 0x427f
	v_lshlrev_b32_e32 v107, 1, v1
	v_lshlrev_b32_e32 v108, 1, v0
	v_add_u32_e32 v109, 0x4000, v94
	v_lshlrev_b32_e32 v110, 1, v3
	v_add_u32_e32 v111, 0x400, v94
	v_lshlrev_b32_e32 v112, 1, v2
	v_add_u32_e32 v113, 0x4400, v94
	v_add_u32_e32 v114, 0x800, v94
	v_lshlrev_b32_e32 v115, 1, v4
	v_add_u32_e32 v116, 0x4800, v94
	v_lshlrev_b32_e32 v117, 1, v5
	v_add_u32_e32 v118, 0xc00, v94
	v_lshlrev_b32_e32 v119, 1, v6
	v_add_u32_e32 v120, 0x4c00, v94
	s_movk_i32 s13, 0x407f
	s_mov_b32 s20, 0xfe03f81
	s_branch .LBB0_864
.LBB0_863:
	s_add_i32 s21, s21, s84
	s_add_i32 s11, s11, s12
	s_cmp_lt_i32 s21, s76
	s_barrier
	s_cbranch_scc0 .LBB0_876
	s_cmp_eq_u32 s84, 0x200
	s_cbranch_scc1 .LBB0_876

.LBB0_1074:
	s_or_b64 exec, exec, s[4:5]
	s_add_u32 s3, s30, 0x21c0000
	s_addc_u32 s7, s31, 0
	s_andn2_b64 vcc, exec, s[8:9]
	s_waitcnt lgkmcnt(0)
	s_barrier
	s_cbranch_vccnz .LBB0_1083
	v_xor_b32_e32 v0, v153, v166
	v_and_b32_e32 v4, 48, v157
	v_lshl_or_b32 v129, v154, 5, v167
	v_lshlrev_b32_e32 v0, 3, v0
	v_lshlrev_b32_e32 v1, 4, v152
	v_sub_u32_e32 v4, 0, v4
	v_and_b32_e32 v148, 24, v0
	v_mul_u32_u24_e32 v0, 0xb00, v129
	v_lshl_or_b32 v150, v154, 11, v1
	v_and_b32_e32 v1, 0x4f, v153
	v_and_b32_e32 v2, 0x1c0, v162
	v_bitop3_b32 v151, v153, 48, v4 bitop3:0x48
	v_or_b32_e32 v0, v0, v148
	v_mov_b32_e32 v133, 0
	v_or_b32_e32 v3, v2, v159
	v_lshl_or_b32 v167, v1, 6, v151
	v_and_or_b32 v2, v155, 12, v2
	v_lshlrev_b32_e32 v1, 1, v1
	v_add_u32_e32 v132, 0xb000, v0
	v_lshlrev_b32_e32 v166, 6, v3
	v_lshl_or_b32 v168, v2, 8, v1
	v_lshlrev_b32_e32 v2, 1, v0
	v_mov_b32_e32 v3, v133
	v_lshlrev_b32_e32 v1, 4, v159
	s_add_u32 s4, s30, 0x27e0040
	v_lshl_add_u64 v[134:135], s[30:31], 0, v[2:3]
	v_lshlrev_b32_e32 v2, 1, v132
	v_lshl_or_b32 v172, v158, 8, v1
	v_or_b32_e32 v149, 16, v129
	v_or_b32_e32 v169, 32, v168
	v_or_b32_e32 v170, 64, v168
	v_or_b32_e32 v171, 0x60, v168
	s_addc_u32 s5, s31, 0
	v_lshl_add_u64 v[136:137], s[30:31], 0, v[2:3]
	s_lshl_b32 s10, s84, 7
	v_or_b32_e32 v173, 0x8000, v172
	v_mov_b32_e32 v174, 0x427f
	v_lshlrev_b32_e32 v175, 1, v0
	v_add_u32_e32 v176, 0x2000, v150
	v_add_u32_e32 v177, 0x4000, v150
	v_add_u32_e32 v178, 0x400, v150
	v_lshlrev_b64 v[138:139], 1, v[132:133]
	v_add_u32_e32 v179, 0x2400, v150
	v_add_u32_e32 v180, 0x4400, v150
	v_mov_b32_e32 v181, 0x1600
	s_mov_b64 s[8:9], 0x21c0040
	s_mov_b64 s[14:15], 0x2270040
	s_mov_b32 s11, s2
	s_cmp_eq_u32 s84, 0x200
	s_cbranch_scc0 .Lx9d_go
	s_and_b32 s12, s2, 7
	s_lshr_b32 s13, s2, 3
	s_and_b32 s11, s13, 3
	s_lshr_b32 s13, s13, 2
	s_mul_i32 s11, s11, 0x85
	s_lshl_b32 s13, s13, 3
	s_add_i32 s11, s11, s12
	s_add_i32 s11, s11, s13
	s_sub_i32 s12, s11, s2
	s_lshl_b32 s12, s12, 7
	v_add_u32_e32 v165, s12, v165
.Lx9d_go:
.LBB0_1076:
	s_mul_hi_i32 s12, s11, 0xf6603d99
	s_add_i32 s12, s12, s11
	s_lshr_b32 s13, s12, 31
	s_ashr_i32 s12, s12, 7
	s_add_i32 s13, s12, s13
	s_mul_i32 s12, s13, 0xffffff7b
	s_add_i32 s12, s12, s11
	s_lshl_b32 s21, s12, 7
	v_add_u32_e32 v0, s21, v129
	v_med3_i32 v0, v0, 0, v174
	s_lshl_b32 s20, s13, 8
	s_mul_i32 s12, s13, 0x160000
	v_mul_u32_u24_e32 v0, 0xb00, v0
	s_mul_hi_i32 s19, s20, 0x1600
	s_add_u32 s18, s3, s12
	v_or_b32_e32 v132, v0, v148
	v_add_u32_e32 v0, s21, v149
	s_addc_u32 s19, s7, s19
	s_or_b32 s12, s20, 0x80
	v_med3_i32 v0, v0, 0, v174
	v_lshlrev_b64 v[2:3], 1, v[132:133]
	v_readfirstlane_b32 s21, v150
	s_mul_i32 s22, s12, 0x1600
	v_mul_u32_u24_e32 v0, 0xb00, v0
	v_lshl_add_u64 v[4:5], s[60:61], 0, v[2:3]
	s_mov_b32 m0, s21
	v_readfirstlane_b32 s21, v176
	s_mul_hi_i32 s23, s12, 0x1600
	s_add_u32 s22, s3, s22
	v_or_b32_e32 v0, v0, v148
	global_load_lds_dwordx4 v[4:5], off
	s_mov_b32 m0, s21
	v_readfirstlane_b32 s21, v177
	v_mov_b32_e32 v1, v133
	s_addc_u32 s23, s7, s23
	global_load_lds_dwordx4 v175, s[18:19]
	s_mov_b32 m0, s21
	v_lshlrev_b64 v[0:1], 1, v[0:1]
	v_readfirstlane_b32 s21, v178
	global_load_lds_dwordx4 v175, s[22:23]
	v_lshl_add_u64 v[4:5], s[60:61], 0, v[0:1]
	s_mov_b32 m0, s21
	v_lshl_add_u64 v[140:141], s[4:5], 0, v[2:3]
	global_load_lds_dwordx4 v[4:5], off
	v_lshl_add_u64 v[4:5], s[18:19], 0, v[138:139]
	v_readfirstlane_b32 s18, v179
	s_mov_b32 m0, s18
	v_readfirstlane_b32 s18, v180
	global_load_lds_dwordx4 v[4:5], off
	v_lshl_add_u64 v[4:5], s[22:23], 0, v[138:139]
	s_mov_b32 m0, s18
	v_mad_i64_i32 v[144:145], s[18:19], s20, v181, v[134:135]
	global_load_lds_dwordx4 v[4:5], off
	v_mad_i64_i32 v[146:147], s[18:19], s20, v181, v[136:137]
	v_lshl_add_u64 v[142:143], s[4:5], 0, v[0:1]
	v_lshl_add_u64 v[248:249], v[144:145], 0, s[14:15]
	v_lshl_add_u64 v[250:251], v[146:147], 0, s[14:15]
	v_lshl_add_u64 v[144:145], v[144:145], 0, s[8:9]
	v_lshl_add_u64 v[146:147], v[146:147], 0, s[8:9]
	v_add_u32_e32 v254, v151, v166
	v_readfirstlane_b32 s25, v150
	s_add_i32 s24, s25, 0x6000
	s_mov_b32 m0, s24
	s_nop 0
	global_load_lds_dwordx4 v[140:141], off
	v_lshl_add_u64 v[140:141], v[140:141], 0, 64
	s_add_i32 m0, s24, 0x2000
	s_nop 0
	global_load_lds_dwordx4 v[144:145], off
	v_lshl_add_u64 v[144:145], v[144:145], 0, 64
	s_add_i32 m0, s24, 0x4000
	s_nop 0
	global_load_lds_dwordx4 v[248:249], off
	v_lshl_add_u64 v[248:249], v[248:249], 0, 64
	s_add_i32 m0, s24, 0x400
	s_nop 0
	global_load_lds_dwordx4 v[142:143], off
	v_lshl_add_u64 v[142:143], v[142:143], 0, 64
	s_add_i32 m0, s24, 0x2400
	s_nop 0
	global_load_lds_dwordx4 v[146:147], off
	v_lshl_add_u64 v[146:147], v[146:147], 0, 64
	s_add_i32 m0, s24, 0x4400
	s_nop 0
	global_load_lds_dwordx4 v[250:251], off
	v_lshl_add_u64 v[250:251], v[250:251], 0, 64
	v_mov_b32_e32 v0, 0
	v_mov_b32_e32 v1, 0
	v_mov_b32_e32 v2, 0
	v_mov_b32_e32 v3, 0
	v_mov_b32_e32 v4, 0
	v_mov_b32_e32 v5, 0
	v_mov_b32_e32 v6, 0
	v_mov_b32_e32 v7, 0
	v_mov_b32_e32 v8, 0
	v_mov_b32_e32 v9, 0
	v_mov_b32_e32 v10, 0
	v_mov_b32_e32 v11, 0
	v_mov_b32_e32 v12, 0
	v_mov_b32_e32 v13, 0
	v_mov_b32_e32 v14, 0
	v_mov_b32_e32 v15, 0
	v_mov_b32_e32 v16, 0
	v_mov_b32_e32 v17, 0
	v_mov_b32_e32 v18, 0
	v_mov_b32_e32 v19, 0
	v_mov_b32_e32 v20, 0
	v_mov_b32_e32 v21, 0
	v_mov_b32_e32 v22, 0
	v_mov_b32_e32 v23, 0
	v_mov_b32_e32 v24, 0
	v_mov_b32_e32 v25, 0
	v_mov_b32_e32 v26, 0
	v_mov_b32_e32 v27, 0
	v_mov_b32_e32 v28, 0
	v_mov_b32_e32 v29, 0
	v_mov_b32_e32 v30, 0
	v_mov_b32_e32 v31, 0
	v_mov_b32_e32 v32, 0
	v_mov_b32_e32 v33, 0
	v_mov_b32_e32 v34, 0
	v_mov_b32_e32 v35, 0
	v_mov_b32_e32 v36, 0
	v_mov_b32_e32 v37, 0
	v_mov_b32_e32 v38, 0
	v_mov_b32_e32 v39, 0
	v_mov_b32_e32 v40, 0
	v_mov_b32_e32 v41, 0
	v_mov_b32_e32 v42, 0
	v_mov_b32_e32 v43, 0
	v_mov_b32_e32 v44, 0
	v_mov_b32_e32 v45, 0
	v_mov_b32_e32 v46, 0
	v_mov_b32_e32 v47, 0
	v_mov_b32_e32 v48, 0
	v_mov_b32_e32 v49, 0
	v_mov_b32_e32 v50, 0
	v_mov_b32_e32 v51, 0
	v_mov_b32_e32 v52, 0
	v_mov_b32_e32 v53, 0
	v_mov_b32_e32 v54, 0
	v_mov_b32_e32 v55, 0
	v_mov_b32_e32 v56, 0
	v_mov_b32_e32 v57, 0
	v_mov_b32_e32 v58, 0
	v_mov_b32_e32 v59, 0
	v_mov_b32_e32 v60, 0
	v_mov_b32_e32 v61, 0
	v_mov_b32_e32 v62, 0
	v_mov_b32_e32 v63, 0
	v_mov_b32_e32 v64, 0
	v_mov_b32_e32 v65, 0
	v_mov_b32_e32 v66, 0
	v_mov_b32_e32 v67, 0
	v_mov_b32_e32 v68, 0
	v_mov_b32_e32 v69, 0
	v_mov_b32_e32 v70, 0
	v_mov_b32_e32 v71, 0
	v_mov_b32_e32 v72, 0
	v_mov_b32_e32 v73, 0
	v_mov_b32_e32 v74, 0
	v_mov_b32_e32 v75, 0
	v_mov_b32_e32 v76, 0
	v_mov_b32_e32 v77, 0
	v_mov_b32_e32 v78, 0
	v_mov_b32_e32 v79, 0
	v_mov_b32_e32 v80, 0
	v_mov_b32_e32 v81, 0
	v_mov_b32_e32 v82, 0
	v_mov_b32_e32 v83, 0
	v_mov_b32_e32 v84, 0
	v_mov_b32_e32 v85, 0
	v_mov_b32_e32 v86, 0
	v_mov_b32_e32 v87, 0
	v_mov_b32_e32 v88, 0
	v_mov_b32_e32 v89, 0
	v_mov_b32_e32 v90, 0
	v_mov_b32_e32 v91, 0
	v_mov_b32_e32 v92, 0
	v_mov_b32_e32 v93, 0
	v_mov_b32_e32 v94, 0
	v_mov_b32_e32 v95, 0
	v_mov_b32_e32 v96, 0
	v_mov_b32_e32 v97, 0
	v_mov_b32_e32 v98, 0
	v_mov_b32_e32 v99, 0
	v_mov_b32_e32 v100, 0
	v_mov_b32_e32 v101, 0
	v_mov_b32_e32 v102, 0
	v_mov_b32_e32 v103, 0
	v_mov_b32_e32 v104, 0
	v_mov_b32_e32 v105, 0
	v_mov_b32_e32 v106, 0
	v_mov_b32_e32 v107, 0
	v_mov_b32_e32 v108, 0
	v_mov_b32_e32 v109, 0
	v_mov_b32_e32 v110, 0
	v_mov_b32_e32 v111, 0
	v_mov_b32_e32 v112, 0
	v_mov_b32_e32 v113, 0
	v_mov_b32_e32 v114, 0
	v_mov_b32_e32 v115, 0
	v_mov_b32_e32 v116, 0
	v_mov_b32_e32 v117, 0
	v_mov_b32_e32 v118, 0
	v_mov_b32_e32 v119, 0
	v_mov_b32_e32 v120, 0
	v_mov_b32_e32 v121, 0
	v_mov_b32_e32 v122, 0
	v_mov_b32_e32 v123, 0
	v_mov_b32_e32 v124, 0
	v_mov_b32_e32 v125, 0
	v_mov_b32_e32 v126, 0
	v_mov_b32_e32 v127, 0
	s_mov_b32 s21, 0
	s_mov_b32 s22, 0
	s_mov_b32 s23, 0xc000

.LBB0_1083:
	s_cmp_eq_u32 s84, 0x200
	s_cbranch_scc0 .Lx9s_orig
	s_cmp_lt_u32 s2, 64
	s_cbranch_scc0 .LBB0_1090
	s_and_b32 s4, s2, 7
	s_cmp_lt_u32 s4, 5
	s_cbranch_scc0 .LBB0_1090
	s_lshr_b32 s5, s2, 4
	s_mul_i32 s5, s5, 0x85
	s_add_i32 s5, s5, s4
	s_addk_i32 s5, 0xfe80
	s_lshl_b32 s5, s5, 1
	s_bfe_u32 s4, s2, 0x10003
	s_or_b32 s2, s5, s4
	s_branch .Lx9s_ent

.Lx9s_ent:
	v_lshl_or_b32 v96, v154, 5, v163
	v_or_b32_e32 v98, 8, v96
	v_lshrrev_b32_e32 v2, 1, v98
	v_xor_b32_e32 v2, v2, v153
	v_lshlrev_b32_e32 v2, 3, v2
	v_or_b32_e32 v101, 24, v96
	v_mul_u32_u24_e32 v1, 0xb00, v96
	v_and_b32_e32 v99, 56, v2
	v_lshrrev_b32_e32 v3, 1, v101
	v_or_b32_e32 v2, v1, v99
	v_xor_b32_e32 v3, v3, v153
	v_lshlrev_b32_e32 v0, 3, v164
	s_movk_i32 s4, 0xb00
	v_add_u32_e32 v64, 0x5800, v2
	v_mov_b32_e32 v2, 0xb000
	v_lshlrev_b32_e32 v3, 3, v3
	v_and_b32_e32 v97, 56, v0
	v_mad_u32_u24 v2, v96, s4, v2
	v_and_b32_e32 v102, 56, v3
	v_or_b32_e32 v66, v97, v2
	v_or_b32_e32 v2, v2, v102
	v_add_u32_e32 v68, 0x5800, v2
	v_lshlrev_b32_e32 v2, 4, v152
	v_or_b32_e32 v0, v97, v1
	v_lshl_or_b32 v103, v154, 12, v2
	v_and_b32_e32 v2, 0x4f, v153
	v_and_b32_e32 v3, 0x1c0, v162
	v_mov_b32_e32 v71, 0
	v_or_b32_e32 v4, v3, v159
	v_lshlrev_b32_e32 v106, 7, v2
	v_and_or_b32 v3, v155, 12, v3
	v_lshlrev_b32_e32 v2, 1, v2
	v_lshlrev_b32_e32 v70, 1, v0
	v_lshl_or_b32 v108, v3, 8, v2
	v_lshl_add_u64 v[2:3], s[30:31], 0, v[70:71]
	s_mov_b64 s[8:9], 0x21c0080
	v_lshl_add_u64 v[72:73], v[2:3], 0, s[8:9]
	v_lshlrev_b32_e32 v2, 1, v64
	v_mov_b32_e32 v3, v71
	v_lshl_add_u64 v[2:3], s[30:31], 0, v[2:3]
	v_add_u32_e32 v70, 0x16000, v70
	v_lshl_add_u64 v[74:75], v[2:3], 0, s[8:9]
	v_lshl_add_u64 v[2:3], s[30:31], 0, v[70:71]
	v_lshl_add_u64 v[76:77], v[2:3], 0, s[8:9]
	v_or_b32_e32 v1, v1, v102
	v_mov_b32_e32 v2, 0x21000
	v_lshl_add_u32 v70, v1, 1, v2
	s_add_u32 s4, s30, 0x27e0080
	v_lshl_add_u64 v[2:3], s[30:31], 0, v[70:71]
	s_addc_u32 s5, s31, 0
	v_lshl_add_u64 v[78:79], v[2:3], 0, s[8:9]
	v_lshlrev_b32_e32 v1, 4, v159
	s_lshl_b32 s8, s75, 7
	v_bitop3_b32 v5, v160, v162, 7 bitop3:0x78
	v_lshl_or_b32 v109, v158, 8, v1
	v_subrev_u32_e32 v1, s8, v158
	v_or_b32_e32 v100, 16, v96
	v_mov_b32_e32 v65, v71
	v_mov_b32_e32 v67, v71
	v_mov_b32_e32 v69, v71
	v_lshlrev_b32_e32 v104, 4, v5
	v_lshlrev_b32_e32 v105, 7, v4
	v_lshlrev_b32_e32 v107, 4, v161
	s_lshl_b32 s10, s2, 7
	s_lshl_b32 s11, s84, 7
	v_add_u32_e32 v110, 0x10a00, v1
	v_mov_b32_e32 v111, 0x427f
	v_lshlrev_b32_e32 v112, 1, v0
	v_add_u32_e32 v113, 0x4000, v103
	v_add_u32_e32 v114, 0x400, v103
	v_add_u32_e32 v115, 0x4400, v103
	v_add_u32_e32 v116, 0x800, v103
	v_add_u32_e32 v117, 0x4800, v103
	v_add_u32_e32 v118, 0xc00, v103
	v_add_u32_e32 v119, 0x4c00, v103
	v_mov_b32_e32 v120, 0x1600

.LBB0_1088:
	v_ashrrev_i32_e32 v3, 31, v2
	v_lshlrev_b64 v[4:5], 11, v[2:3]
	v_lshl_add_u64 v[12:13], v[0:1], 0, v[4:5]
	global_load_dwordx4 v[4:7], v[12:13], off
	v_add_u32_e32 v3, s8, v109
	ds_read_b128 v[8:11], v3
	s_addk_i32 s8, 0x1000
	v_add_u32_e32 v2, 16, v2
	s_cmpk_lg_u32 s8, 0x8000
	s_waitcnt lgkmcnt(0)
	v_cvt_f32_f16_e32 v14, v8
	v_cvt_f32_f16_sdwa v15, v8 dst_sel:DWORD dst_unused:UNUSED_PAD src0_sel:WORD_1
	v_cvt_f32_f16_e32 v8, v9
	v_cvt_f32_f16_sdwa v9, v9 dst_sel:DWORD dst_unused:UNUSED_PAD src0_sel:WORD_1
	v_cvt_f32_f16_e32 v16, v10
	v_cvt_f32_f16_sdwa v17, v10 dst_sel:DWORD dst_unused:UNUSED_PAD src0_sel:WORD_1
	v_cvt_f32_f16_e32 v10, v11
	v_cvt_f32_f16_sdwa v11, v11 dst_sel:DWORD dst_unused:UNUSED_PAD src0_sel:WORD_1
	s_waitcnt vmcnt(0)
	v_cvt_f32_f16_e32 v18, v4
	v_cvt_f32_f16_sdwa v19, v4 dst_sel:DWORD dst_unused:UNUSED_PAD src0_sel:WORD_1
	v_cvt_f32_f16_e32 v4, v5
	v_cvt_f32_f16_sdwa v5, v5 dst_sel:DWORD dst_unused:UNUSED_PAD src0_sel:WORD_1
	v_cvt_f32_f16_e32 v20, v6
	v_cvt_f32_f16_sdwa v21, v6 dst_sel:DWORD dst_unused:UNUSED_PAD src0_sel:WORD_1
	v_cvt_f32_f16_e32 v6, v7
	v_cvt_f32_f16_sdwa v7, v7 dst_sel:DWORD dst_unused:UNUSED_PAD src0_sel:WORD_1
	v_pk_add_f32 v[14:15], v[14:15], v[18:19]
	v_pk_add_f32 v[4:5], v[8:9], v[4:5]
	v_pk_add_f32 v[8:9], v[16:17], v[20:21]
	v_pk_add_f32 v[6:7], v[10:11], v[6:7]
	v_cvt_pk_f16_f32 v5, v4, v5
	v_cvt_pk_f16_f32 v7, v6, v7
	v_cvt_pk_f16_f32 v6, v8, v9
	v_cvt_pk_f16_f32 v4, v14, v15
	global_store_dwordx4 v[12:13], v[4:7], off
	s_cbranch_scc1 .LBB0_1088
	s_add_i32 s2, s2, s84
	s_add_i32 s10, s10, s11
	s_barrier
	s_cmp_eq_u32 s84, 0x200
	s_cbranch_scc1 .LBB0_1090
	s_cmp_lt_i32 s2, s76
	s_cbranch_scc1 .LBB0_1085
